# MoBA: next tile's K/V LDS-DMA issued after the QK fragment reads of the current tile instead of at the tile head (skipping waves issue it in their skip path)
# speedup vs baseline: 1.0089x; 1.0031x over previous
; __device__ void moba_item(const P& p, int bh, int qt, char* smem) {
;     ...
;   auto step = [&](const int tt, u32x4 (&rk)[4], u32x4 (&rv)[4]) __attribute__((always_inline)) {
;     __syncthreads();
; #pragma unroll
;     for (int i = 0; i < 4; ++i) {
;       const int row = kr + 16 * i;
;       const int f = ((row >> 3) & 3) * 4 + (row & 3);
;       *(u32x4*)(sK + row * 256 + ((kc ^ f) << 4)) = rk[i];
;       const int vrow = vr + 32 * i;
;       *(u32x4*)(sV + vrow * 128 + ((vc ^ (vrow & 7)) << 4)) = rv[i];
;     }
;     __syncthreads();
;     if (tt + 2 < ntiles) {
;       const int k1 = (tt + 2) * 64;
; #pragma unroll
;       for (int i = 0; i < 4; ++i) {
;         rk[i] = *(const u32x4*)(Kp + (size_t)(k1 + kr + 16 * i) * 128 + kc * 8);
;         rv[i] = *(const u32x4*)(VT + (size_t)(vr + 32 * i) * 4096 + k1 + vc * 8);
;       }
;     }
;     const int blk = tt >> 2;
;     const bool own = (blk == qblk);
;     const bool rowvalid = own || ((mymask >> blk) & 1u);
;     if (__any(rowvalid)) {
;       const int key0 = tt * 64;
;       f32x4 sacc[2][2];
; #pragma unroll
;       for (int st = 0; st < 2; ++st)
; #pragma unroll
;         for (int kt = 0; kt < 2; ++kt) {
;           sacc[st][kt] = (f32x4){0.f, 0.f, 0.f, 0.f};
;           const int row = 32 * st + 8 * (li >> 2) + 4 * kt + (li & 3);
; #pragma unroll
;           for (int kk = 0; kk < 4; ++kk) {
;             const bf16x8 kf = *(const bf16x8*)(sK + row * 256 + (((kk * 4 + g) ^ li) << 4));
;             sacc[st][kt] = __builtin_amdgcn_mfma_f32_16x16x32_bf16(kf, qf[kk], sacc[st][kt], 0, 0, 0);
;           }
;         }
.LBB0_616:
	s_lshr_b32 s6, s27, 2
	s_cmp_eq_u32 s6, s41
	s_cselect_b64 s[0:1], -1, 0
	s_lshl_b32 s6, 1, s6
	v_and_b32_e32 v0, s6, v149
	v_cmp_ne_u32_e32 vcc, 0, v0
	s_or_b64 s[6:7], s[0:1], vcc
	s_mov_b64 vcc, s[6:7]
	s_cbranch_vccz .LBB0_625
	v_add_u32_e32 v0, v155, v151
	v_add_u32_e32 v2, v155, v178
	v_add_u32_e32 v3, v155, v179
	v_add_u32_e32 v168, v155, v180
	s_cmp_eq_u32 s40, s27
	s_cselect_b64 s[0:1], -1, 0
	s_and_b64 vcc, exec, s[0:1]
	s_mov_b64 s[10:11], s[0:1]
	ds_read_b128 v[194:197], v0
	ds_read_b128 v[198:201], v0 offset:1024
	ds_read_b128 v[202:205], v0 offset:8192
	ds_read_b128 v[220:223], v0 offset:9216
	ds_read_b128 v[224:227], v2
	ds_read_b128 v[228:231], v2 offset:1024
	ds_read_b128 v[232:235], v2 offset:8192
	ds_read_b128 v[4:7], v2 offset:9216
	ds_read_b128 v[8:11], v3
	ds_read_b128 v[12:15], v3 offset:1024
	ds_read_b128 v[16:19], v3 offset:8192
	ds_read_b128 v[164:167], v3 offset:9216
	s_cmp_ge_i32 s27, s40
	s_cbranch_scc1 .Lmoba_skipA
	s_add_i32 s32, s25, 64
	v_readfirstlane_b32 s98, v152
	v_readfirstlane_b32 s99, v153
	s_lshl_b32 s57, s32, 8
	s_add_u32 s98, s98, s57
	s_addc_u32 s99, s99, 0
	s_add_u32 m0, s79, 0x8000
	s_nop 0
	global_load_lds_dwordx4 v252, s[98:99]
	s_add_u32 m0, s79, 0x9000
	s_add_u32 s98, s98, 0x1000
	s_addc_u32 s99, s99, 0
	global_load_lds_dwordx4 v253, s[98:99]
	s_add_u32 m0, s79, 0xa000
	s_add_u32 s98, s98, 0x1000
	s_addc_u32 s99, s99, 0
	global_load_lds_dwordx4 v252, s[98:99]
	s_add_u32 m0, s79, 0xb000
	s_add_u32 s98, s98, 0x1000
	s_addc_u32 s99, s99, 0
	global_load_lds_dwordx4 v253, s[98:99]
	v_readfirstlane_b32 s98, v156
	v_readfirstlane_b32 s99, v157
	s_lshl_b32 s57, s32, 1
	s_add_u32 s98, s98, s57
	s_addc_u32 s99, s99, 0
	s_add_u32 m0, s79, 0xc000
	s_nop 0
	global_load_lds_dwordx4 v254, s[98:99]
	s_add_u32 m0, s79, 0xd000
	s_add_u32 s98, s98, 0x40000
	s_addc_u32 s99, s99, 0
	global_load_lds_dwordx4 v254, s[98:99]
	s_add_u32 m0, s79, 0xe000
	s_add_u32 s98, s98, 0x40000
	s_addc_u32 s99, s99, 0
	global_load_lds_dwordx4 v254, s[98:99]
	s_add_u32 m0, s79, 0xf000
	s_add_u32 s98, s98, 0x40000
	s_addc_u32 s99, s99, 0
	global_load_lds_dwordx4 v254, s[98:99]
	.Lmoba_skipA:
	s_waitcnt lgkmcnt(8)
	v_mfma_f32_16x16x32_bf16 v[132:135], v[194:197], v[20:23], 0
	v_mfma_f32_16x16x32_bf16 v[140:143], v[198:201], v[20:23], 0
	v_mfma_f32_16x16x32_bf16 v[136:139], v[202:205], v[20:23], 0
	v_mfma_f32_16x16x32_bf16 v[144:147], v[220:223], v[20:23], 0
	ds_read_b128 v[194:197], v168
	ds_read_b128 v[198:201], v168 offset:1024
	ds_read_b128 v[202:205], v168 offset:8192
	ds_read_b128 v[220:223], v168 offset:9216
	s_waitcnt lgkmcnt(8)
	v_mfma_f32_16x16x32_bf16 v[132:135], v[224:227], v[24:27], v[132:135]
	v_mfma_f32_16x16x32_bf16 v[140:143], v[228:231], v[24:27], v[140:143]
	v_mfma_f32_16x16x32_bf16 v[136:139], v[232:235], v[24:27], v[136:139]
	v_mfma_f32_16x16x32_bf16 v[144:147], v[4:7], v[24:27], v[144:147]
	s_waitcnt lgkmcnt(4)
	v_mfma_f32_16x16x32_bf16 v[132:135], v[8:11], v[28:31], v[132:135]
	v_mfma_f32_16x16x32_bf16 v[140:143], v[12:15], v[28:31], v[140:143]
	v_mfma_f32_16x16x32_bf16 v[136:139], v[16:19], v[28:31], v[136:139]
	v_mfma_f32_16x16x32_bf16 v[144:147], v[164:167], v[28:31], v[144:147]
	s_waitcnt lgkmcnt(0)
	v_mfma_f32_16x16x32_bf16 v[132:135], v[194:197], v[32:35], v[132:135]
	v_mfma_f32_16x16x32_bf16 v[140:143], v[198:201], v[32:35], v[140:143]
	v_mfma_f32_16x16x32_bf16 v[136:139], v[202:205], v[32:35], v[136:139]
	v_mfma_f32_16x16x32_bf16 v[144:147], v[220:223], v[32:35], v[144:147]
	s_nop 7
	s_cbranch_vccnz .LBB0_620
	v_cndmask_b32_e64 v4, v244, 0, s[6:7]
	s_mov_b32 s28, 0x3e0293ee
	v_pk_fma_f32 v[164:165], v[134:135], s[28:29], v[4:5] op_sel_hi:[1,0,0]
	v_pk_fma_f32 v[168:169], v[142:143], s[28:29], v[4:5] op_sel_hi:[1,0,0]
	v_pk_fma_f32 v[2:3], v[132:133], s[28:29], v[4:5] op_sel_hi:[1,0,0]
	v_max_f32_e32 v0, v164, v165
	v_pk_fma_f32 v[166:167], v[140:141], s[28:29], v[4:5] op_sel_hi:[1,0,0]
	v_max_f32_e32 v170, v168, v169
	v_max3_f32 v0, v2, v3, v0
	v_max3_f32 v170, v166, v167, v170
	s_mov_b32 s10, 0xff800000
	v_pk_fma_f32 v[172:173], v[138:139], s[28:29], v[4:5] op_sel_hi:[1,0,0]
	v_max3_f32 v0, v0, s10, v170
	v_pk_fma_f32 v[170:171], v[136:137], s[28:29], v[4:5] op_sel_hi:[1,0,0]
	v_max_f32_e32 v174, v172, v173
	v_pk_fma_f32 v[176:177], v[146:147], s[28:29], v[4:5] op_sel_hi:[1,0,0]
	v_max3_f32 v190, v170, v171, v174
	v_pk_fma_f32 v[174:175], v[144:145], s[28:29], v[4:5] op_sel_hi:[1,0,0]
	v_max_f32_e32 v191, v176, v177
	v_max3_f32 v191, v174, v175, v191
	v_max3_f32 v0, v0, v190, v191
	s_mov_b64 s[10:11], 0

; __device__ void moba_item(const P& p, int bh, int qt, char* smem) {
;     ...
;     if (tt + 2 < ntiles) {
;       const int k1 = (tt + 2) * 64;
; #pragma unroll
;       for (int i = 0; i < 4; ++i) {
;         rk[i] = *(const u32x4*)(Kp + (size_t)(k1 + kr + 16 * i) * 128 + kc * 8);
;         rv[i] = *(const u32x4*)(VT + (size_t)(vr + 32 * i) * 4096 + k1 + vc * 8);
;       }
;     }
;     ...
;   for (int tt = 0; tt < ntiles; tt += 2) {
;     step(tt, rkA, rvA);
;     if (tt + 1 < ntiles) step(tt + 1, rkB, rvB);
;   }
.Lmoba_lateB:
	s_cmp_lg_u32 s8, 0
	s_cbranch_scc1 .Lmoba_skipB2
	s_add_i32 s32, s25, 128
	v_readfirstlane_b32 s98, v152
	v_readfirstlane_b32 s99, v153
	s_lshl_b32 s57, s32, 8
	s_add_u32 s98, s98, s57
	s_addc_u32 s99, s99, 0
	s_add_u32 m0, s79, 0x0
	s_nop 0
	global_load_lds_dwordx4 v252, s[98:99]
	s_add_u32 m0, s79, 0x1000
	s_add_u32 s98, s98, 0x1000
	s_addc_u32 s99, s99, 0
	global_load_lds_dwordx4 v253, s[98:99]
	s_add_u32 m0, s79, 0x2000
	s_add_u32 s98, s98, 0x1000
	s_addc_u32 s99, s99, 0
	global_load_lds_dwordx4 v252, s[98:99]
	s_add_u32 m0, s79, 0x3000
	s_add_u32 s98, s98, 0x1000
	s_addc_u32 s99, s99, 0
	global_load_lds_dwordx4 v253, s[98:99]
	v_readfirstlane_b32 s98, v156
	v_readfirstlane_b32 s99, v157
	s_lshl_b32 s57, s32, 1
	s_add_u32 s98, s98, s57
	s_addc_u32 s99, s99, 0
	s_add_u32 m0, s79, 0x4000
	s_nop 0
	global_load_lds_dwordx4 v254, s[98:99]
	s_add_u32 m0, s79, 0x5000
	s_add_u32 s98, s98, 0x40000
	s_addc_u32 s99, s99, 0
	global_load_lds_dwordx4 v254, s[98:99]
	s_add_u32 m0, s79, 0x6000
	s_add_u32 s98, s98, 0x40000
	s_addc_u32 s99, s99, 0
	global_load_lds_dwordx4 v254, s[98:99]
	s_add_u32 m0, s79, 0x7000
	s_add_u32 s98, s98, 0x40000
	s_addc_u32 s99, s99, 0
	global_load_lds_dwordx4 v254, s[98:99]
.Lmoba_skipB2:
	s_branch .LBB0_612
.LBB0_625:
	s_cmp_ge_i32 s27, s40
	s_cbranch_scc1 .Lmoba_skipA2
	s_add_i32 s32, s25, 64
	v_readfirstlane_b32 s98, v152
	v_readfirstlane_b32 s99, v153
	s_lshl_b32 s57, s32, 8
	s_add_u32 s98, s98, s57
	s_addc_u32 s99, s99, 0
	s_add_u32 m0, s79, 0x8000
	s_nop 0
	global_load_lds_dwordx4 v252, s[98:99]
	s_add_u32 m0, s79, 0x9000
	s_add_u32 s98, s98, 0x1000
	s_addc_u32 s99, s99, 0
	global_load_lds_dwordx4 v253, s[98:99]
	s_add_u32 m0, s79, 0xa000
	s_add_u32 s98, s98, 0x1000
	s_addc_u32 s99, s99, 0
	global_load_lds_dwordx4 v252, s[98:99]
	s_add_u32 m0, s79, 0xb000
	s_add_u32 s98, s98, 0x1000
	s_addc_u32 s99, s99, 0
	global_load_lds_dwordx4 v253, s[98:99]
	v_readfirstlane_b32 s98, v156
	v_readfirstlane_b32 s99, v157
	s_lshl_b32 s57, s32, 1
	s_add_u32 s98, s98, s57
	s_addc_u32 s99, s99, 0
	s_add_u32 m0, s79, 0xc000
	s_nop 0
	global_load_lds_dwordx4 v254, s[98:99]
	s_add_u32 m0, s79, 0xd000
	s_add_u32 s98, s98, 0x40000
	s_addc_u32 s99, s99, 0
	global_load_lds_dwordx4 v254, s[98:99]
	s_add_u32 m0, s79, 0xe000
	s_add_u32 s98, s98, 0x40000
	s_addc_u32 s99, s99, 0
	global_load_lds_dwordx4 v254, s[98:99]
	s_add_u32 m0, s79, 0xf000
	s_add_u32 s98, s98, 0x40000
	s_addc_u32 s99, s99, 0
	global_load_lds_dwordx4 v254, s[98:99]

; __device__ void moba_item(const P& p, int bh, int qt, char* smem) {
;     ...
;     if (tt + 2 < ntiles) {
;       const int k1 = (tt + 2) * 64;
; #pragma unroll
;       for (int i = 0; i < 4; ++i) {
;         rk[i] = *(const u32x4*)(Kp + (size_t)(k1 + kr + 16 * i) * 128 + kc * 8);
;         rv[i] = *(const u32x4*)(VT + (size_t)(vr + 32 * i) * 4096 + k1 + vc * 8);
;       }
;     }
;     const int blk = tt >> 2;
;     const bool own = (blk == qblk);
;     const bool rowvalid = own || ((mymask >> blk) & 1u);
;     if (__any(rowvalid)) {
;       const int key0 = tt * 64;
;       f32x4 sacc[2][2];
; #pragma unroll
;       for (int st = 0; st < 2; ++st)
; #pragma unroll
;         for (int kt = 0; kt < 2; ++kt) {
;           sacc[st][kt] = (f32x4){0.f, 0.f, 0.f, 0.f};
;           const int row = 32 * st + 8 * (li >> 2) + 4 * kt + (li & 3);
; #pragma unroll
;           for (int kk = 0; kk < 4; ++kk) {
;             const bf16x8 kf = *(const bf16x8*)(sK + row * 256 + (((kk * 4 + g) ^ li) << 4));
;             sacc[st][kt] = __builtin_amdgcn_mfma_f32_16x16x32_bf16(kf, qf[kk], sacc[st][kt], 0, 0, 0);
;           }
;         }
;       const bool diag = (tt == ntiles - 1);
;       float mx = -INFINITY;
;       if (diag || !__all(rowvalid)) {
; #pragma unroll
;         for (int st = 0; st < 2; ++st)
; #pragma unroll
;           for (int kt = 0; kt < 2; ++kt)
; #pragma unroll
;             for (int r = 0; r < 4; ++r) {
;               const int key = key0 + 32 * st + 8 * g + 4 * kt + r;
;               bool ok = rowvalid && (!diag || key <= qpos);
;               const float sv = ok ? sacc[st][kt][r] * SC : -INFINITY;
;               sacc[st][kt][r] = sv;
;               mx = fmaxf(mx, sv);
;             }
;       } else {
; #pragma unroll
;         for (int st = 0; st < 2; ++st)
; #pragma unroll
;           for (int kt = 0; kt < 2; ++kt) {
;             sacc[st][kt] *= SC;
;             mx = fmaxf(mx, fmaxf(fmaxf(sacc[st][kt][0], sacc[st][kt][1]), fmaxf(sacc[st][kt][2], sacc[st][kt][3])));
;           }
;       }
.LBB0_628:
	v_cndmask_b32_e64 v0, 0, 1, s[6:7]
	v_cmp_ne_u32_e32 vcc, 0, v0
	s_cbranch_vccz .Lmoba_lateB
	v_add_u32_e32 v2, v155, v151
	v_add_u32_e32 v3, v155, v178
	v_add_u32_e32 v168, v155, v179
	v_add_u32_e32 v169, v155, v180
	s_cmp_eq_u32 s24, s27
	s_cselect_b64 s[0:1], -1, 0
	s_and_b64 vcc, exec, s[0:1]
	s_mov_b64 s[10:11], s[0:1]
	ds_read_b128 v[194:197], v2 offset:32768
	ds_read_b128 v[198:201], v2 offset:33792
	ds_read_b128 v[202:205], v2 offset:40960
	ds_read_b128 v[220:223], v2 offset:41984
	ds_read_b128 v[224:227], v3 offset:32768
	ds_read_b128 v[228:231], v3 offset:33792
	ds_read_b128 v[232:235], v3 offset:40960
	ds_read_b128 v[4:7], v3 offset:41984
	ds_read_b128 v[8:11], v168 offset:32768
	ds_read_b128 v[12:15], v168 offset:33792
	ds_read_b128 v[16:19], v168 offset:40960
	ds_read_b128 v[164:167], v168 offset:41984
	s_cmp_lg_u32 s8, 0
	s_cbranch_scc1 .Lmoba_skipB
	s_add_i32 s32, s25, 128
	v_readfirstlane_b32 s98, v152
	v_readfirstlane_b32 s99, v153
	s_lshl_b32 s57, s32, 8
	s_add_u32 s98, s98, s57
	s_addc_u32 s99, s99, 0
	s_add_u32 m0, s79, 0x0
	s_nop 0
	global_load_lds_dwordx4 v252, s[98:99]
	s_add_u32 m0, s79, 0x1000
	s_add_u32 s98, s98, 0x1000
	s_addc_u32 s99, s99, 0
	global_load_lds_dwordx4 v253, s[98:99]
	s_add_u32 m0, s79, 0x2000
	s_add_u32 s98, s98, 0x1000
	s_addc_u32 s99, s99, 0
	global_load_lds_dwordx4 v252, s[98:99]
	s_add_u32 m0, s79, 0x3000
	s_add_u32 s98, s98, 0x1000
	s_addc_u32 s99, s99, 0
	global_load_lds_dwordx4 v253, s[98:99]
	v_readfirstlane_b32 s98, v156
	v_readfirstlane_b32 s99, v157
	s_lshl_b32 s57, s32, 1
	s_add_u32 s98, s98, s57
	s_addc_u32 s99, s99, 0
	s_add_u32 m0, s79, 0x4000
	s_nop 0
	global_load_lds_dwordx4 v254, s[98:99]
	s_add_u32 m0, s79, 0x5000
	s_add_u32 s98, s98, 0x40000
	s_addc_u32 s99, s99, 0
	global_load_lds_dwordx4 v254, s[98:99]
	s_add_u32 m0, s79, 0x6000
	s_add_u32 s98, s98, 0x40000
	s_addc_u32 s99, s99, 0
	global_load_lds_dwordx4 v254, s[98:99]
	s_add_u32 m0, s79, 0x7000
	s_add_u32 s98, s98, 0x40000
	s_addc_u32 s99, s99, 0
	global_load_lds_dwordx4 v254, s[98:99]
	.Lmoba_skipB:
	s_waitcnt lgkmcnt(8)
	v_mfma_f32_16x16x32_bf16 v[132:135], v[194:197], v[20:23], 0
	v_mfma_f32_16x16x32_bf16 v[140:143], v[198:201], v[20:23], 0
	v_mfma_f32_16x16x32_bf16 v[136:139], v[202:205], v[20:23], 0
	v_mfma_f32_16x16x32_bf16 v[144:147], v[220:223], v[20:23], 0
	ds_read_b128 v[194:197], v169 offset:32768
	ds_read_b128 v[198:201], v169 offset:33792
	ds_read_b128 v[202:205], v169 offset:40960
	ds_read_b128 v[220:223], v169 offset:41984
	s_waitcnt lgkmcnt(8)
	v_mfma_f32_16x16x32_bf16 v[132:135], v[224:227], v[24:27], v[132:135]
	v_mfma_f32_16x16x32_bf16 v[140:143], v[228:231], v[24:27], v[140:143]
	v_mfma_f32_16x16x32_bf16 v[136:139], v[232:235], v[24:27], v[136:139]
	v_mfma_f32_16x16x32_bf16 v[144:147], v[4:7], v[24:27], v[144:147]
	s_waitcnt lgkmcnt(4)
	v_mfma_f32_16x16x32_bf16 v[132:135], v[8:11], v[28:31], v[132:135]
	v_mfma_f32_16x16x32_bf16 v[140:143], v[12:15], v[28:31], v[140:143]
	v_mfma_f32_16x16x32_bf16 v[136:139], v[16:19], v[28:31], v[136:139]
	v_mfma_f32_16x16x32_bf16 v[144:147], v[164:167], v[28:31], v[144:147]
	s_waitcnt lgkmcnt(0)
	v_mfma_f32_16x16x32_bf16 v[132:135], v[194:197], v[32:35], v[132:135]
	v_mfma_f32_16x16x32_bf16 v[140:143], v[198:201], v[32:35], v[140:143]
	v_mfma_f32_16x16x32_bf16 v[136:139], v[202:205], v[32:35], v[136:139]
	v_mfma_f32_16x16x32_bf16 v[144:147], v[220:223], v[32:35], v[144:147]
	s_nop 7
	s_cbranch_vccnz .LBB0_632
	v_cndmask_b32_e64 v4, v244, 0, s[6:7]
	s_mov_b32 s28, 0x3e0293ee
	v_pk_fma_f32 v[164:165], v[134:135], s[28:29], v[4:5] op_sel_hi:[1,0,0]
	v_pk_fma_f32 v[2:3], v[132:133], s[28:29], v[4:5] op_sel_hi:[1,0,0]
	v_max_f32_e32 v166, v164, v165
	v_pk_fma_f32 v[168:169], v[142:143], s[28:29], v[4:5] op_sel_hi:[1,0,0]
	v_max3_f32 v170, v2, v3, v166
	v_pk_fma_f32 v[166:167], v[140:141], s[28:29], v[4:5] op_sel_hi:[1,0,0]
	v_max_f32_e32 v171, v168, v169
	v_max3_f32 v171, v166, v167, v171
	s_mov_b32 s10, 0xff800000
	v_pk_fma_f32 v[172:173], v[138:139], s[28:29], v[4:5] op_sel_hi:[1,0,0]
	v_max3_f32 v189, v170, s10, v171
	v_pk_fma_f32 v[170:171], v[136:137], s[28:29], v[4:5] op_sel_hi:[1,0,0]
	v_max_f32_e32 v174, v172, v173
	v_pk_fma_f32 v[176:177], v[146:147], s[28:29], v[4:5] op_sel_hi:[1,0,0]
	v_max3_f32 v191, v170, v171, v174
	v_pk_fma_f32 v[174:175], v[144:145], s[28:29], v[4:5] op_sel_hi:[1,0,0]
	v_max_f32_e32 v192, v176, v177
	v_max3_f32 v192, v174, v175, v192
	v_max3_f32 v189, v189, v191, v192
	s_mov_b64 s[10:11], 0
